# placement experiment: G1 tile loop and later code shifted +8 B relative to v93
# baseline (speedup 1.0000x reference)
;     DI bool next(int i, Unit& u) const { if (i >= 4) return false; u.pm = pm; u.pn = i; return true; }
; #define PG8_STAGE(bufoff, gbase, voff) do { _Pragma("unroll") for (int _i = 0; _i < 2; ++_i) \
;         __builtin_amdgcn_global_load_lds((const unsigned*)((const char*)(gbase) + (voff)[_i]), (LAS unsigned*)(lds + (bufoff) + ldsw + _i * 8192), 16, 0, 0); } while (0)
; #define PG8_WAIT_V(n) asm volatile("s_waitcnt vmcnt(" #n ")" ::: "memory")
; #define PG8_BAR __builtin_amdgcn_s_barrier()
; template <class Epi, class Sched>
; DI void gemm_phase(ldsp lds, const Gemm g, const Sched& S, const Epi& E, const int tid) {
;     ...
;     for (int i = 0; i < 2; ++i) { int R, C; stage_rc(tid * 16 + i * 8192, R, C); const int Rb = Epi::PERM ? ((R & ~31) + perm32(R & 31)) : R;
;         voffA[i] = (unsigned)(R * K + C) * 2u; voffB[i] = (unsigned)(Rb * K + C) * 2u; }
;     const size_t kstep = (size_t)(BK * 2);
;     const size_t hstep = (size_t)HALF * K * 2;
;     const size_t tstep = 2 * hstep;
;     const unsigned ldsw = (unsigned)wid * 1024u;
;     const int aoff = lds_byte(wr * 64 + fr, fq * 8), boff = lds_byte(wc * 32 + fr, fq * 8);
;     ...
;     Unit cur, nxt; int ui = 0;
;     if (!S.next(0, cur)) return;
;     f32x4 acc[2][2][4][2];
; #pragma unroll
;     for (int a = 0; a < 2; ++a)
; #pragma unroll
;         for (int b = 0; b < 2; ++b)
; #pragma unroll
;             for (int m = 0; m < 4; ++m)
; #pragma unroll
;                 for (int n = 0; n < 2; ++n) acc[a][b][m][n] = (f32x4){0.f, 0.f, 0.f, 0.f};
;     bf16x8 At[4][2], B0[2][2], B1[2][2];
;     const char* cA = (const char*)g.A + (size_t)cur.pm * tstep; const char* cB = (const char*)g.Bt + (size_t)cur.pn * tstep;
;     PG8_STAGE(PG8_SB(0, 0), cB, voffB); PG8_STAGE(PG8_SA(0, 0), cA, voffA); PG8_STAGE(PG8_SB(0, 1), cB + hstep, voffB); PG8_STAGE(PG8_SA(0, 1), cA + hstep, voffA);
;     if (wr == 1) PG8_BAR;
;     PG8_WAIT_V(4); PG8_BAR;
;     PG8_STAGE(PG8_SB(1, 0), cB + kstep, voffB); PG8_STAGE(PG8_SA(1, 0), cA + kstep, voffA); PG8_STAGE(PG8_SB(1, 1), cB + hstep + kstep, voffB);
;     PG8_WAIT_V(6); PG8_BAR;
.LBB0_659:
	s_sext_i32_i16 s64, s26
	v_readlane_b32 s26, v255, 9
	s_lshl_b32 s26, s26, 27
	s_and_b32 s38, s26, 0x8000000
	s_and_b64 s[26:27], s[42:43], exec
	s_cselect_b32 s26, 0, s38
	s_lshl_b32 s26, s26, 1
	v_readlane_b32 s38, v251, 15
	v_readlane_b32 s39, v251, 16
	s_add_u32 s26, s38, s26
	v_lshrrev_b32_e32 v16, 1, v32
	s_addc_u32 s27, s39, 0
	v_and_b32_e32 v16, 24, v16
	s_lshl_b32 s36, s36, 5
	v_lshlrev_b32_e32 v17, 1, v16
	v_lshlrev_b32_e32 v18, 2, v155
	s_and_b32 s38, s36, 0x60
	s_add_i32 m0, s31, 0x18000
	v_lshl_add_u64 v[6:7], v[6:7], 0, s[96:97]
	v_lshl_or_b32 v13, s37, 6, v155
	v_lshl_or_b32 v17, v155, 6, v17
	s_lshl_b32 s37, s37, 13
	v_and_b32_e32 v18, 32, v18
	s_lshl_b32 s36, s38, 7
	s_waitcnt vmcnt(4)
	s_barrier
	global_load_lds_dwordx4 v[6:7], off
	v_lshl_add_u64 v[4:5], v[4:5], 0, s[96:97]
	s_add_i32 m0, s31, 0x1a000
	s_add_i32 s62, s31, 0x8000
	s_add_i32 s63, s31, 0xa000
	v_bitop3_b32 v33, s36, v17, v18 bitop3:0xf6
	global_load_lds_dwordx4 v[4:5], off
	v_lshl_add_u64 v[2:3], v[2:3], 0, s[96:97]
	s_mov_b32 m0, s62
	s_add_u32 s36, s48, 0x40080
	v_bitop3_b32 v19, v17, s37, v18 bitop3:0xde
	global_load_lds_dwordx4 v[2:3], off
	v_lshl_add_u64 v[0:1], v[0:1], 0, s[96:97]
	s_mov_b32 m0, s63
	s_addc_u32 s37, s49, 0
	global_load_lds_dwordx4 v[0:1], off
	s_add_i32 m0, s31, 0x1c000
	v_lshl_add_u64 v[0:1], s[36:37], 0, v[136:137]
	global_load_lds_dwordx4 v[0:1], off
	v_lshl_add_u64 v[0:1], s[36:37], 0, v[30:31]
	s_add_i32 m0, s31, 0x1e000
	s_mov_b32 s61, 0
	global_load_lds_dwordx4 v[0:1], off
	v_lshlrev_b32_e32 v0, 14, v14
	v_and_b32_e32 v0, 0xffff8000, v0
	v_lshl_add_u32 v0, v11, 11, v0
	v_and_b32_e32 v1, 1, v14
	v_lshl_or_b32 v0, v1, 6, v0
	v_lshl_add_u32 v140, v15, 1, v0
	v_lshlrev_b32_e32 v0, 14, v8
	v_and_b32_e32 v0, 0xffff8000, v0
	s_waitcnt vmcnt(6)
	v_lshl_add_u32 v0, v9, 11, v0
	v_and_b32_e32 v1, 1, v8
	v_lshl_or_b32 v0, v1, 6, v0
	v_or_b32_e32 v144, s38, v16
	v_mov_b32_e32 v141, v12
	v_lshl_add_u32 v142, v10, 1, v0
	v_mov_b32_e32 v143, v12
	v_add_u32_e32 v145, 0, v19
	s_barrier
	v_mul_lo_u32 v224, v13, s14
	v_add_lshl_u32 v224, v224, v144, 1
	s_lshl_b32 s100, s14, 5
	s_nop 0
	s_nop 0
